# prologue init_row: the four 16-byte loads of a row issued together with counted waits (was load, wait, store, load, ...); wave sum via DPP
# speedup vs baseline: 1.0081x; 1.0081x over previous
; __device__ __forceinline__ unsigned pk2(float lo, float hi) { f32x2_t v = {lo, hi}; bf16x2_t b = __builtin_convertvector(v, bf16x2_t); return __builtin_bit_cast(unsigned, b); }
; __device__ __forceinline__ void init_row(const float* src, float* hrow, bf16_t* hb, float* ssp, float* ssm, int lane) {
;     float s = 0.f;
; #pragma unroll
;     for (int j = 0; j < 4; ++j) { const f32x4 v = *((const f32x4*)src + lane + 64 * j); s += (v.x * v.x + v.y * v.y) + (v.z * v.z + v.w * v.w);
;         u32x2 o; o.x = pk2(v.x, v.y); o.y = pk2(v.z, v.w); *((u32x2*)hb + lane + 64 * j) = o; }
;     s = wave_sum(s); if (lane < 16) ssp[lane] = lane == 0 ? s : 0.f;
;     if (ssm) ssm[lane] = lane == 0 ? s : 0.f;
.LBB0_51:
	s_andn2_saveexec_b64 s[0:1], s[0:1]
	v_ashrrev_i32_e32 v13, 31, v12
	s_or_b64 exec, exec, s[0:1]
	v_lshlrev_b64 v[12:13], 12, v[12:13]
	v_lshl_add_u64 v[12:13], v[16:17], 0, v[12:13]
	v_lshl_add_u64 v[16:17], v[12:13], 0, v[8:9]
	global_load_dwordx4 v[12:15], v[16:17], off
	global_load_dwordx4 v[24:27], v[16:17], off offset:1024
	global_load_dwordx4 v[28:31], v[16:17], off offset:2048
	global_load_dwordx4 v[32:35], v[16:17], off offset:3072
	v_ashrrev_i32_e32 v11, 31, v10
	v_lshlrev_b64 v[38:39], 11, v[10:11]
	v_lshl_add_u64 v[36:37], v[2:3], 0, v[38:39]
	s_waitcnt vmcnt(3)
	v_cvt_pk_bf16_f32 v38, v12, v13
	v_cvt_pk_bf16_f32 v39, v14, v15
	global_store_dwordx2 v[36:37], v[38:39], off
	v_mul_f32_e32 v0, v13, v13
	v_mul_f32_e32 v7, v15, v15
	v_fmac_f32_e32 v0, v12, v12
	v_fmac_f32_e32 v7, v14, v14
	v_add_f32_e32 v0, v0, v7
	s_waitcnt vmcnt(3)
	v_cvt_pk_bf16_f32 v40, v24, v25
	v_cvt_pk_bf16_f32 v41, v26, v27
	global_store_dwordx2 v[36:37], v[40:41], off offset:512
	v_mul_f32_e32 v7, v25, v25
	v_mul_f32_e32 v12, v27, v27
	v_fmac_f32_e32 v7, v24, v24
	v_fmac_f32_e32 v12, v26, v26
	v_add_f32_e32 v7, v7, v12
	v_add_f32_e32 v0, v0, v7
	s_waitcnt vmcnt(3)
	v_cvt_pk_bf16_f32 v42, v28, v29
	v_cvt_pk_bf16_f32 v43, v30, v31
	global_store_dwordx2 v[36:37], v[42:43], off offset:1024
	v_mul_f32_e32 v7, v29, v29
	v_mul_f32_e32 v12, v31, v31
	v_fmac_f32_e32 v7, v28, v28
	v_fmac_f32_e32 v12, v30, v30
	v_add_f32_e32 v7, v7, v12
	v_add_f32_e32 v0, v0, v7
	s_waitcnt vmcnt(3)
	v_mul_f32_e32 v7, v33, v33
	v_mul_f32_e32 v12, v35, v35
	v_fmac_f32_e32 v7, v32, v32
	v_fmac_f32_e32 v12, v34, v34
	v_add_f32_e32 v7, v7, v12
	v_add_f32_e32 v0, v0, v7
	v_cvt_pk_bf16_f32 v12, v32, v33
	v_cvt_pk_bf16_f32 v13, v34, v35
	global_store_dwordx2 v[36:37], v[12:13], off offset:1536
	s_nop 1
	v_add_f32_dpp v0, v0, v0 quad_perm:[1,0,3,2] row_mask:0xf bank_mask:0xf
	s_nop 1
	v_add_f32_dpp v0, v0, v0 quad_perm:[2,3,0,1] row_mask:0xf bank_mask:0xf
	s_nop 1
	v_add_f32_dpp v0, v0, v0 row_half_mirror row_mask:0xf bank_mask:0xf
	s_nop 1
	v_add_f32_dpp v0, v0, v0 row_mirror row_mask:0xf bank_mask:0xf
	ds_bpermute_b32 v7, v22, v0
	s_waitcnt lgkmcnt(0)
	v_add_f32_e32 v0, v0, v7
	v_mov_b32_e32 v7, v0
	s_nop 1
	v_permlane32_swap_b32_e32 v7, v0
	v_add_f32_e32 v0, v0, v7
	v_cndmask_b32_e64 v14, 0, v0, s[4:5]
	s_and_saveexec_b64 s[0:1], vcc
	s_cbranch_execz .LBB0_55
	v_lshlrev_b64 v[12:13], 6, v[10:11]
	v_lshl_add_u64 v[12:13], v[4:5], 0, v[12:13]
	global_store_dword v[12:13], v14, off
